# v82 plus hand-written 256x128 16x16x32 tile on the 256-workgroup path of OUT1 (16-byte residual loads and stores)
# speedup vs baseline: 1.0603x; 1.0082x over previous
.LBB0_182:
	s_and_b32 s36, s34, 56
	s_or_b32 s36, s36, s83
	s_lshl_b32 s36, s36, 8
	s_and_b32 s35, s34, 7
	s_lshl_b32 s35, s35, 7
	s_lshl_b32 s55, s36, 11
	s_add_u32 s28, s50, s55
	s_addc_u32 s29, s51, 0
	s_lshl_b32 s55, s35, 11
	s_add_u32 s30, s48, s55
	s_addc_u32 s31, s49, 0
	v_readfirstlane_b32 s55, v200
	s_lshr_b32 s55, s55, 6
	s_lshl_b32 s32, s55, 11
	s_add_u32 s32, s32, 16
	s_lshl_b32 s37, s55, 10
	s_add_u32 s37, s37, 0x4010
	s_lshl_b32 s55, s55, 15
	s_add_u32 s30, s30, s55
	s_addc_u32 s31, s31, 0
	s_lshl_b32 s55, s55, 1
	s_add_u32 s28, s28, s55
	s_addc_u32 s29, s29, 0
	v_bfe_u32 v173, v200, 4, 2
	v_sub_u32_e32 v173, 0, v173
	v_and_b32_e32 v173, 3, v173
	v_and_b32_e32 v172, 3, v200
	v_xor_b32_e32 v172, v172, v173
	v_bfe_u32 v173, v200, 2, 4
	v_lshlrev_b32_e32 v173, 11, v173
	v_lshl_or_b32 v170, v172, 4, v173
	v_add_u32_e32 v171, 0x8000, v170
	v_bfe_u32 v172, v200, 2, 2
	v_sub_u32_e32 v172, 0, v172
	v_and_b32_e32 v172, 3, v172
	v_bfe_u32 v173, v200, 4, 2
	v_xor_b32_e32 v172, v172, v173
	v_and_b32_e32 v173, 15, v200
	v_bfe_u32 v174, v200, 7, 2
	v_lshl_or_b32 v174, v174, 6, v173
	v_lshlrev_b32_e32 v174, 6, v174
	v_lshl_or_b32 v164, v172, 4, v174
	v_bfe_u32 v174, v200, 6, 1
	v_lshl_or_b32 v174, v174, 6, v173
	v_lshlrev_b32_e32 v174, 6, v174
	v_lshl_or_b32 v165, v172, 4, v174
	v_add_u32_e32 v165, 0x4000, v165
	v_bfe_u32 v172, v200, 6, 1
	v_bfe_u32 v173, v200, 4, 2
	v_lshlrev_b32_e32 v172, 6, v172
	v_lshl_or_b32 v172, v173, 2, v172
	v_add_u32_e32 v172, s35, v172
	v_lshlrev_b32_e32 v172, 2, v172
	global_load_dwordx4 v[132:135], v172, s[42:43]
	global_load_dwordx4 v[136:139], v172, s[42:43] offset:64
	global_load_dwordx4 v[140:143], v172, s[42:43] offset:128
	global_load_dwordx4 v[144:147], v172, s[42:43] offset:192
	s_mov_b32 s53, 0x0
	s_add_u32 m0, s32, s53
	s_nop 0
	global_load_lds_dwordx4 v170, s[28:29]
	s_add_u32 m0, s32, s53
	s_add_u32 m0, m0, 0x400
	s_nop 0
	global_load_lds_dwordx4 v171, s[28:29]
	s_add_u32 m0, s37, s53
	s_nop 0
	global_load_lds_dwordx4 v170, s[30:31]
	s_add_u32 s28, s28, 64
	s_addc_u32 s29, s29, 0
	s_add_u32 s30, s30, 64
	s_addc_u32 s31, s31, 0
	s_mov_b32 s53, 0x6000
	s_add_u32 m0, s32, s53
	s_nop 0
	global_load_lds_dwordx4 v170, s[28:29]
	s_add_u32 m0, s32, s53
	s_add_u32 m0, m0, 0x400
	s_nop 0
	global_load_lds_dwordx4 v171, s[28:29]
	s_add_u32 m0, s37, s53
	s_nop 0
	global_load_lds_dwordx4 v170, s[30:31]
	s_add_u32 s28, s28, 64
	s_addc_u32 s29, s29, 0
	s_add_u32 s30, s30, 64
	s_addc_u32 s31, s31, 0
	s_mov_b32 s53, 0xc000
	s_add_u32 m0, s32, s53
	s_nop 0
	global_load_lds_dwordx4 v170, s[28:29]
	s_add_u32 m0, s32, s53
	s_add_u32 m0, m0, 0x400
	s_nop 0
	global_load_lds_dwordx4 v171, s[28:29]
	s_add_u32 m0, s37, s53
	s_nop 0
	global_load_lds_dwordx4 v170, s[30:31]
	s_add_u32 s28, s28, 64
	s_addc_u32 s29, s29, 0
	s_add_u32 s30, s30, 64
	s_addc_u32 s31, s31, 0
	s_mov_b32 s53, 0x12000
	s_add_u32 m0, s32, s53
	s_nop 0
	global_load_lds_dwordx4 v170, s[28:29]
	s_add_u32 m0, s32, s53
	s_add_u32 m0, m0, 0x400
	s_nop 0
	global_load_lds_dwordx4 v171, s[28:29]
	s_add_u32 m0, s37, s53
	s_nop 0
	global_load_lds_dwordx4 v170, s[30:31]
	s_add_u32 s28, s28, 64
	s_addc_u32 s29, s29, 0
	s_add_u32 s30, s30, 64
	s_addc_u32 s31, s31, 0
	s_waitcnt vmcnt(12)
	v_mov_b32_e32 v4, v132
	v_mov_b32_e32 v5, v133
	v_mov_b32_e32 v6, v134
	v_mov_b32_e32 v7, v135
	v_mov_b32_e32 v8, v136
	v_mov_b32_e32 v9, v137
	v_mov_b32_e32 v10, v138
	v_mov_b32_e32 v11, v139
	v_mov_b32_e32 v12, v140
	v_mov_b32_e32 v13, v141
	v_mov_b32_e32 v14, v142
	v_mov_b32_e32 v15, v143
	v_mov_b32_e32 v16, v144
	v_mov_b32_e32 v17, v145
	v_mov_b32_e32 v18, v146
	v_mov_b32_e32 v19, v147
	v_mov_b32_e32 v20, v132
	v_mov_b32_e32 v21, v133
	v_mov_b32_e32 v22, v134
	v_mov_b32_e32 v23, v135
	v_mov_b32_e32 v24, v136
	v_mov_b32_e32 v25, v137
	v_mov_b32_e32 v26, v138
	v_mov_b32_e32 v27, v139
	v_mov_b32_e32 v28, v140
	v_mov_b32_e32 v29, v141
	v_mov_b32_e32 v30, v142
	v_mov_b32_e32 v31, v143
	v_mov_b32_e32 v32, v144
	v_mov_b32_e32 v33, v145
	v_mov_b32_e32 v34, v146
	v_mov_b32_e32 v35, v147
	v_mov_b32_e32 v36, v132
	v_mov_b32_e32 v37, v133
	v_mov_b32_e32 v38, v134
	v_mov_b32_e32 v39, v135
	v_mov_b32_e32 v40, v136
	v_mov_b32_e32 v41, v137
	v_mov_b32_e32 v42, v138
	v_mov_b32_e32 v43, v139
	v_mov_b32_e32 v44, v140
	v_mov_b32_e32 v45, v141
	v_mov_b32_e32 v46, v142
	v_mov_b32_e32 v47, v143
	v_mov_b32_e32 v48, v144
	v_mov_b32_e32 v49, v145
	v_mov_b32_e32 v50, v146
	v_mov_b32_e32 v51, v147
	v_mov_b32_e32 v52, v132
	v_mov_b32_e32 v53, v133
	v_mov_b32_e32 v54, v134
	v_mov_b32_e32 v55, v135
	v_mov_b32_e32 v56, v136
	v_mov_b32_e32 v57, v137
	v_mov_b32_e32 v58, v138
	v_mov_b32_e32 v59, v139
	v_mov_b32_e32 v60, v140
	v_mov_b32_e32 v61, v141
	v_mov_b32_e32 v62, v142
	v_mov_b32_e32 v63, v143
	v_mov_b32_e32 v64, v144
	v_mov_b32_e32 v65, v145
	v_mov_b32_e32 v66, v146
	v_mov_b32_e32 v67, v147
	s_waitcnt vmcnt(9)
	s_barrier
	s_mov_b32 s52, 0
	s_mov_b32 s54, 0
	s_nop 1
	v_add_u32_e32 v168, s52, v165
	v_add_u32_e32 v169, s52, v164
	ds_read_b128 v[132:135], v168 offset:16
	ds_read_b128 v[136:139], v168 offset:1040
	ds_read_b128 v[140:143], v168 offset:2064
	ds_read_b128 v[144:147], v168 offset:3088
	ds_read_b128 v[184:187], v169 offset:16
	ds_read_b128 v[188:191], v169 offset:1040
	s_waitcnt lgkmcnt(0)
.Lt_out1v:
	v_add_u32_e32 v169, s52, v164
	v_mfma_f32_16x16x32_f16 v[4:7], v[132:135], v[184:187], v[4:7]
	ds_read_b128 v[192:195], v169 offset:2064
	v_mfma_f32_16x16x32_f16 v[8:11], v[136:139], v[184:187], v[8:11]
	ds_read_b128 v[196:199], v169 offset:3088
	v_mfma_f32_16x16x32_f16 v[12:15], v[140:143], v[184:187], v[12:15]
	v_mfma_f32_16x16x32_f16 v[16:19], v[144:147], v[184:187], v[16:19]
	v_mfma_f32_16x16x32_f16 v[20:23], v[132:135], v[188:191], v[20:23]
	v_mfma_f32_16x16x32_f16 v[24:27], v[136:139], v[188:191], v[24:27]
	v_mfma_f32_16x16x32_f16 v[28:31], v[140:143], v[188:191], v[28:31]
	v_mfma_f32_16x16x32_f16 v[32:35], v[144:147], v[188:191], v[32:35]
	s_waitcnt vmcnt(6) lgkmcnt(0)
	s_barrier
	s_add_i32 s53, s52, 0x6000
	s_cmp_lg_u32 s52, 0x12000
	s_cselect_b32 s53, s53, 0
	v_add_u32_e32 v168, s53, v165
	v_add_u32_e32 v169, s53, v164
	v_mfma_f32_16x16x32_f16 v[36:39], v[132:135], v[192:195], v[36:39]
	ds_read_b128 v[148:151], v168 offset:16
	ds_read_b128 v[184:187], v169 offset:16
	v_mfma_f32_16x16x32_f16 v[40:43], v[136:139], v[192:195], v[40:43]
	ds_read_b128 v[152:155], v168 offset:1040
	ds_read_b128 v[188:191], v169 offset:1040
	v_mfma_f32_16x16x32_f16 v[44:47], v[140:143], v[192:195], v[44:47]
	ds_read_b128 v[156:159], v168 offset:2064
	v_mfma_f32_16x16x32_f16 v[48:51], v[144:147], v[192:195], v[48:51]
	ds_read_b128 v[160:163], v168 offset:3088
	v_mfma_f32_16x16x32_f16 v[52:55], v[132:135], v[196:199], v[52:55]
	s_add_u32 m0, s32, s52
	s_nop 0
	global_load_lds_dwordx4 v170, s[28:29]
	v_mfma_f32_16x16x32_f16 v[56:59], v[136:139], v[196:199], v[56:59]
	s_add_u32 m0, s32, s52
	s_add_u32 m0, m0, 0x400
	s_nop 0
	global_load_lds_dwordx4 v171, s[28:29]
	v_mfma_f32_16x16x32_f16 v[60:63], v[140:143], v[196:199], v[60:63]
	s_add_u32 m0, s37, s52
	s_nop 0
	global_load_lds_dwordx4 v170, s[30:31]
	v_mfma_f32_16x16x32_f16 v[64:67], v[144:147], v[196:199], v[64:67]
	s_waitcnt lgkmcnt(0)
	s_mov_b32 s52, s53
	s_add_u32 s28, s28, 64
	s_addc_u32 s29, s29, 0
	s_add_u32 s30, s30, 64
	s_addc_u32 s31, s31, 0
	v_add_u32_e32 v169, s52, v164
	v_mfma_f32_16x16x32_f16 v[4:7], v[148:151], v[184:187], v[4:7]
	ds_read_b128 v[192:195], v169 offset:2064
	v_mfma_f32_16x16x32_f16 v[8:11], v[152:155], v[184:187], v[8:11]
	ds_read_b128 v[196:199], v169 offset:3088
	v_mfma_f32_16x16x32_f16 v[12:15], v[156:159], v[184:187], v[12:15]
	v_mfma_f32_16x16x32_f16 v[16:19], v[160:163], v[184:187], v[16:19]
	v_mfma_f32_16x16x32_f16 v[20:23], v[148:151], v[188:191], v[20:23]
	v_mfma_f32_16x16x32_f16 v[24:27], v[152:155], v[188:191], v[24:27]
	v_mfma_f32_16x16x32_f16 v[28:31], v[156:159], v[188:191], v[28:31]
	v_mfma_f32_16x16x32_f16 v[32:35], v[160:163], v[188:191], v[32:35]
	s_waitcnt vmcnt(6) lgkmcnt(0)
	s_barrier
	s_add_i32 s53, s52, 0x6000
	s_cmp_lg_u32 s52, 0x12000
	s_cselect_b32 s53, s53, 0
	v_add_u32_e32 v168, s53, v165
	v_add_u32_e32 v169, s53, v164
	v_mfma_f32_16x16x32_f16 v[36:39], v[148:151], v[192:195], v[36:39]
	ds_read_b128 v[132:135], v168 offset:16
	ds_read_b128 v[184:187], v169 offset:16
	v_mfma_f32_16x16x32_f16 v[40:43], v[152:155], v[192:195], v[40:43]
	ds_read_b128 v[136:139], v168 offset:1040
	ds_read_b128 v[188:191], v169 offset:1040
	v_mfma_f32_16x16x32_f16 v[44:47], v[156:159], v[192:195], v[44:47]
	ds_read_b128 v[140:143], v168 offset:2064
	v_mfma_f32_16x16x32_f16 v[48:51], v[160:163], v[192:195], v[48:51]
	ds_read_b128 v[144:147], v168 offset:3088
	v_mfma_f32_16x16x32_f16 v[52:55], v[148:151], v[196:199], v[52:55]
	s_add_u32 m0, s32, s52
	s_nop 0
	global_load_lds_dwordx4 v170, s[28:29]
	v_mfma_f32_16x16x32_f16 v[56:59], v[152:155], v[196:199], v[56:59]
	s_add_u32 m0, s32, s52
	s_add_u32 m0, m0, 0x400
	s_nop 0
	global_load_lds_dwordx4 v171, s[28:29]
	v_mfma_f32_16x16x32_f16 v[60:63], v[156:159], v[196:199], v[60:63]
	s_add_u32 m0, s37, s52
	s_nop 0
	global_load_lds_dwordx4 v170, s[30:31]
	v_mfma_f32_16x16x32_f16 v[64:67], v[160:163], v[196:199], v[64:67]
	s_waitcnt lgkmcnt(0)
	s_mov_b32 s52, s53
	s_add_u32 s28, s28, 64
	s_addc_u32 s29, s29, 0
	s_add_u32 s30, s30, 64
	s_addc_u32 s31, s31, 0
	s_add_i32 s54, s54, 2
	s_cmp_lt_u32 s54, 28
	s_cbranch_scc1 .Lt_out1v
	v_add_u32_e32 v169, s52, v164
	v_mfma_f32_16x16x32_f16 v[4:7], v[132:135], v[184:187], v[4:7]
	ds_read_b128 v[192:195], v169 offset:2064
	v_mfma_f32_16x16x32_f16 v[8:11], v[136:139], v[184:187], v[8:11]
	ds_read_b128 v[196:199], v169 offset:3088
	v_mfma_f32_16x16x32_f16 v[12:15], v[140:143], v[184:187], v[12:15]
	v_mfma_f32_16x16x32_f16 v[16:19], v[144:147], v[184:187], v[16:19]
	v_mfma_f32_16x16x32_f16 v[20:23], v[132:135], v[188:191], v[20:23]
	v_mfma_f32_16x16x32_f16 v[24:27], v[136:139], v[188:191], v[24:27]
	v_mfma_f32_16x16x32_f16 v[28:31], v[140:143], v[188:191], v[28:31]
	v_mfma_f32_16x16x32_f16 v[32:35], v[144:147], v[188:191], v[32:35]
	s_waitcnt vmcnt(6) lgkmcnt(0)
	s_barrier
	s_add_i32 s53, s52, 0x6000
	s_cmp_lg_u32 s52, 0x12000
	s_cselect_b32 s53, s53, 0
	v_add_u32_e32 v168, s53, v165
	v_add_u32_e32 v169, s53, v164
	v_mfma_f32_16x16x32_f16 v[36:39], v[132:135], v[192:195], v[36:39]
	ds_read_b128 v[148:151], v168 offset:16
	ds_read_b128 v[184:187], v169 offset:16
	v_mfma_f32_16x16x32_f16 v[40:43], v[136:139], v[192:195], v[40:43]
	ds_read_b128 v[152:155], v168 offset:1040
	ds_read_b128 v[188:191], v169 offset:1040
	v_mfma_f32_16x16x32_f16 v[44:47], v[140:143], v[192:195], v[44:47]
	ds_read_b128 v[156:159], v168 offset:2064
	v_mfma_f32_16x16x32_f16 v[48:51], v[144:147], v[192:195], v[48:51]
	ds_read_b128 v[160:163], v168 offset:3088
	v_mfma_f32_16x16x32_f16 v[52:55], v[132:135], v[196:199], v[52:55]
	v_mfma_f32_16x16x32_f16 v[56:59], v[136:139], v[196:199], v[56:59]
	v_mfma_f32_16x16x32_f16 v[60:63], v[140:143], v[196:199], v[60:63]
	v_mfma_f32_16x16x32_f16 v[64:67], v[144:147], v[196:199], v[64:67]
	s_waitcnt lgkmcnt(0)
	s_mov_b32 s52, s53
	v_add_u32_e32 v169, s52, v164
	v_mfma_f32_16x16x32_f16 v[4:7], v[148:151], v[184:187], v[4:7]
	ds_read_b128 v[192:195], v169 offset:2064
	v_mfma_f32_16x16x32_f16 v[8:11], v[152:155], v[184:187], v[8:11]
	ds_read_b128 v[196:199], v169 offset:3088
	v_mfma_f32_16x16x32_f16 v[12:15], v[156:159], v[184:187], v[12:15]
	v_mfma_f32_16x16x32_f16 v[16:19], v[160:163], v[184:187], v[16:19]
	v_mfma_f32_16x16x32_f16 v[20:23], v[148:151], v[188:191], v[20:23]
	v_mfma_f32_16x16x32_f16 v[24:27], v[152:155], v[188:191], v[24:27]
	v_mfma_f32_16x16x32_f16 v[28:31], v[156:159], v[188:191], v[28:31]
	v_mfma_f32_16x16x32_f16 v[32:35], v[160:163], v[188:191], v[32:35]
	s_waitcnt vmcnt(3) lgkmcnt(0)
	s_barrier
	s_add_i32 s53, s52, 0x6000
	s_cmp_lg_u32 s52, 0x12000
	s_cselect_b32 s53, s53, 0
	v_add_u32_e32 v168, s53, v165
	v_add_u32_e32 v169, s53, v164
	v_mfma_f32_16x16x32_f16 v[36:39], v[148:151], v[192:195], v[36:39]
	ds_read_b128 v[132:135], v168 offset:16
	ds_read_b128 v[184:187], v169 offset:16
	v_mfma_f32_16x16x32_f16 v[40:43], v[152:155], v[192:195], v[40:43]
	ds_read_b128 v[136:139], v168 offset:1040
	ds_read_b128 v[188:191], v169 offset:1040
	v_mfma_f32_16x16x32_f16 v[44:47], v[156:159], v[192:195], v[44:47]
	ds_read_b128 v[140:143], v168 offset:2064
	v_mfma_f32_16x16x32_f16 v[48:51], v[160:163], v[192:195], v[48:51]
	ds_read_b128 v[144:147], v168 offset:3088
	v_mfma_f32_16x16x32_f16 v[52:55], v[148:151], v[196:199], v[52:55]
	v_mfma_f32_16x16x32_f16 v[56:59], v[152:155], v[196:199], v[56:59]
	v_mfma_f32_16x16x32_f16 v[60:63], v[156:159], v[196:199], v[60:63]
	v_mfma_f32_16x16x32_f16 v[64:67], v[160:163], v[196:199], v[64:67]
	s_waitcnt lgkmcnt(0)
	s_mov_b32 s52, s53
	v_add_u32_e32 v169, s52, v164
	v_mfma_f32_16x16x32_f16 v[4:7], v[132:135], v[184:187], v[4:7]
	ds_read_b128 v[192:195], v169 offset:2064
	v_mfma_f32_16x16x32_f16 v[8:11], v[136:139], v[184:187], v[8:11]
	ds_read_b128 v[196:199], v169 offset:3088
	v_mfma_f32_16x16x32_f16 v[12:15], v[140:143], v[184:187], v[12:15]
	v_mfma_f32_16x16x32_f16 v[16:19], v[144:147], v[184:187], v[16:19]
	v_mfma_f32_16x16x32_f16 v[20:23], v[132:135], v[188:191], v[20:23]
	v_mfma_f32_16x16x32_f16 v[24:27], v[136:139], v[188:191], v[24:27]
	v_mfma_f32_16x16x32_f16 v[28:31], v[140:143], v[188:191], v[28:31]
	v_mfma_f32_16x16x32_f16 v[32:35], v[144:147], v[188:191], v[32:35]
	s_waitcnt vmcnt(0) lgkmcnt(0)
	s_barrier
	s_add_i32 s53, s52, 0x6000
	s_cmp_lg_u32 s52, 0x12000
	s_cselect_b32 s53, s53, 0
	v_add_u32_e32 v168, s53, v165
	v_add_u32_e32 v169, s53, v164
	v_mfma_f32_16x16x32_f16 v[36:39], v[132:135], v[192:195], v[36:39]
	ds_read_b128 v[148:151], v168 offset:16
	ds_read_b128 v[184:187], v169 offset:16
	v_mfma_f32_16x16x32_f16 v[40:43], v[136:139], v[192:195], v[40:43]
	ds_read_b128 v[152:155], v168 offset:1040
	ds_read_b128 v[188:191], v169 offset:1040
	v_mfma_f32_16x16x32_f16 v[44:47], v[140:143], v[192:195], v[44:47]
	ds_read_b128 v[156:159], v168 offset:2064
	v_mfma_f32_16x16x32_f16 v[48:51], v[144:147], v[192:195], v[48:51]
	ds_read_b128 v[160:163], v168 offset:3088
	v_mfma_f32_16x16x32_f16 v[52:55], v[132:135], v[196:199], v[52:55]
	v_mfma_f32_16x16x32_f16 v[56:59], v[136:139], v[196:199], v[56:59]
	v_mfma_f32_16x16x32_f16 v[60:63], v[140:143], v[196:199], v[60:63]
	v_mfma_f32_16x16x32_f16 v[64:67], v[144:147], v[196:199], v[64:67]
	s_waitcnt lgkmcnt(0)
	s_mov_b32 s52, s53
	v_add_u32_e32 v169, s52, v164
	v_mfma_f32_16x16x32_f16 v[4:7], v[148:151], v[184:187], v[4:7]
	ds_read_b128 v[192:195], v169 offset:2064
	v_mfma_f32_16x16x32_f16 v[8:11], v[152:155], v[184:187], v[8:11]
	ds_read_b128 v[196:199], v169 offset:3088
	v_mfma_f32_16x16x32_f16 v[12:15], v[156:159], v[184:187], v[12:15]
	v_mfma_f32_16x16x32_f16 v[16:19], v[160:163], v[184:187], v[16:19]
	v_mfma_f32_16x16x32_f16 v[20:23], v[148:151], v[188:191], v[20:23]
	v_mfma_f32_16x16x32_f16 v[24:27], v[152:155], v[188:191], v[24:27]
	v_mfma_f32_16x16x32_f16 v[28:31], v[156:159], v[188:191], v[28:31]
	v_mfma_f32_16x16x32_f16 v[32:35], v[160:163], v[188:191], v[32:35]
	s_waitcnt lgkmcnt(0)
	s_barrier
	v_mfma_f32_16x16x32_f16 v[36:39], v[148:151], v[192:195], v[36:39]
	v_mfma_f32_16x16x32_f16 v[40:43], v[152:155], v[192:195], v[40:43]
	v_mfma_f32_16x16x32_f16 v[44:47], v[156:159], v[192:195], v[44:47]
	v_mfma_f32_16x16x32_f16 v[48:51], v[160:163], v[192:195], v[48:51]
	v_mfma_f32_16x16x32_f16 v[52:55], v[148:151], v[196:199], v[52:55]
	v_mfma_f32_16x16x32_f16 v[56:59], v[152:155], v[196:199], v[56:59]
	v_mfma_f32_16x16x32_f16 v[60:63], v[156:159], v[196:199], v[60:63]
	v_mfma_f32_16x16x32_f16 v[64:67], v[160:163], v[196:199], v[64:67]
	s_sub_u32 s77, s36, 0x1000
	s_lshr_b32 s77, s77, 12
	s_add_u32 s77, s77, 1
	s_cmp_lt_u32 s36, 0x1000
	s_cselect_b32 s77, 0, s77
	s_mul_i32 s77, s77, 0x6000
	s_add_u32 s68, s26, s77
	s_addc_u32 s69, s27, 0
	s_add_u32 s68, s68, 0x20000
	s_addc_u32 s69, s69, 0
	s_lshl_b32 s82, s36, 11
	s_add_u32 s80, s46, s82
	s_addc_u32 s81, s47, 0
	s_lshl_b32 s82, s35, 1
	s_add_u32 s80, s80, s82
	s_addc_u32 s81, s81, 0
	v_and_b32_e32 v172, 15, v200
	v_bfe_u32 v173, v200, 4, 2
	v_bfe_u32 v174, v200, 6, 1
	v_bfe_u32 v175, v200, 7, 2
	v_lshlrev_b32_e32 v176, 6, v174
	v_lshl_or_b32 v176, v173, 2, v176
	v_lshl_or_b32 v175, v175, 6, v172
	v_lshlrev_b32_e32 v175, 11, v175
	v_lshl_add_u32 v177, v176, 1, v175
	v_add_u32_e32 v176, s35, v176
	v_lshlrev_b32_e32 v176, 2, v176
	global_load_dwordx4 v[132:135], v176, s[68:69]
	global_load_dwordx4 v[136:139], v176, s[68:69] offset:64
	global_load_dwordx4 v[140:143], v176, s[68:69] offset:128
	global_load_dwordx4 v[144:147], v176, s[68:69] offset:192
	v_and_b32_e32 v172, 1, v173
	v_mul_u32_u24_e32 v172, 24, v172
	v_add_u32_e32 v177, v177, v172
	v_mov_b32_e32 v178, v177
	global_load_dwordx4 v[184:187], v178, s[80:81]
	global_load_dwordx4 v[188:191], v178, s[80:81] offset:64
	v_add_u32_e32 v178, 0x8000, v178
	global_load_dwordx4 v[192:195], v178, s[80:81]
	global_load_dwordx4 v[196:199], v178, s[80:81] offset:64
	s_waitcnt vmcnt(3)
	v_permlane16_swap_b32_e32 v184, v186
	v_permlane16_swap_b32_e32 v185, v187
	v_cvt_f32_f16_e32 v164, v184
	v_cvt_f32_f16_sdwa v165, v184 dst_sel:DWORD dst_unused:UNUSED_PAD src0_sel:WORD_1
	v_cvt_f32_f16_e32 v166, v185
	v_cvt_f32_f16_sdwa v167, v185 dst_sel:DWORD dst_unused:UNUSED_PAD src0_sel:WORD_1
	v_pk_mul_f32 v[164:165], v[164:165], s[84:85] op_sel_hi:[1,0]
	v_pk_mul_f32 v[166:167], v[166:167], s[84:85] op_sel_hi:[1,0]
	v_pk_fma_f32 v[4:5], v[4:5], v[132:133], v[164:165]
	v_pk_fma_f32 v[6:7], v[6:7], v[134:135], v[166:167]
	v_cvt_pk_f16_f32 v172, v4, v5
	v_cvt_pk_f16_f32 v173, v6, v7
	v_cvt_f32_f16_e32 v164, v186
	v_cvt_f32_f16_sdwa v165, v186 dst_sel:DWORD dst_unused:UNUSED_PAD src0_sel:WORD_1
	v_cvt_f32_f16_e32 v166, v187
	v_cvt_f32_f16_sdwa v167, v187 dst_sel:DWORD dst_unused:UNUSED_PAD src0_sel:WORD_1
	v_pk_mul_f32 v[164:165], v[164:165], s[84:85] op_sel_hi:[1,0]
	v_pk_mul_f32 v[166:167], v[166:167], s[84:85] op_sel_hi:[1,0]
	v_pk_fma_f32 v[8:9], v[8:9], v[136:137], v[164:165]
	v_pk_fma_f32 v[10:11], v[10:11], v[138:139], v[166:167]
	v_cvt_pk_f16_f32 v174, v8, v9
	v_cvt_pk_f16_f32 v175, v10, v11
	s_nop 1
	v_permlane16_swap_b32_e32 v172, v174
	v_permlane16_swap_b32_e32 v173, v175
	global_store_dwordx4 v177, v[172:175], s[80:81]
	s_waitcnt vmcnt(3)
	v_permlane16_swap_b32_e32 v188, v190
	v_permlane16_swap_b32_e32 v189, v191
	v_cvt_f32_f16_e32 v164, v188
	v_cvt_f32_f16_sdwa v165, v188 dst_sel:DWORD dst_unused:UNUSED_PAD src0_sel:WORD_1
	v_cvt_f32_f16_e32 v166, v189
	v_cvt_f32_f16_sdwa v167, v189 dst_sel:DWORD dst_unused:UNUSED_PAD src0_sel:WORD_1
	v_pk_mul_f32 v[164:165], v[164:165], s[84:85] op_sel_hi:[1,0]
	v_pk_mul_f32 v[166:167], v[166:167], s[84:85] op_sel_hi:[1,0]
	v_pk_fma_f32 v[12:13], v[12:13], v[140:141], v[164:165]
	v_pk_fma_f32 v[14:15], v[14:15], v[142:143], v[166:167]
	v_cvt_pk_f16_f32 v228, v12, v13
	v_cvt_pk_f16_f32 v229, v14, v15
	v_cvt_f32_f16_e32 v164, v190
	v_cvt_f32_f16_sdwa v165, v190 dst_sel:DWORD dst_unused:UNUSED_PAD src0_sel:WORD_1
	v_cvt_f32_f16_e32 v166, v191
	v_cvt_f32_f16_sdwa v167, v191 dst_sel:DWORD dst_unused:UNUSED_PAD src0_sel:WORD_1
	v_pk_mul_f32 v[164:165], v[164:165], s[84:85] op_sel_hi:[1,0]
	v_pk_mul_f32 v[166:167], v[166:167], s[84:85] op_sel_hi:[1,0]
	v_pk_fma_f32 v[16:17], v[16:17], v[144:145], v[164:165]
	v_pk_fma_f32 v[18:19], v[18:19], v[146:147], v[166:167]
	v_cvt_pk_f16_f32 v230, v16, v17
	v_cvt_pk_f16_f32 v231, v18, v19
	s_nop 1
	v_permlane16_swap_b32_e32 v228, v230
	v_permlane16_swap_b32_e32 v229, v231
	global_store_dwordx4 v177, v[228:231], s[80:81] offset:64
	v_add_u32_e32 v177, 0x8000, v177
	v_add_u32_e32 v178, 0x8000, v178
	global_load_dwordx4 v[184:187], v178, s[80:81]
	global_load_dwordx4 v[188:191], v178, s[80:81] offset:64
	s_waitcnt vmcnt(5)
	v_permlane16_swap_b32_e32 v192, v194
	v_permlane16_swap_b32_e32 v193, v195
	v_cvt_f32_f16_e32 v164, v192
	v_cvt_f32_f16_sdwa v165, v192 dst_sel:DWORD dst_unused:UNUSED_PAD src0_sel:WORD_1
	v_cvt_f32_f16_e32 v166, v193
	v_cvt_f32_f16_sdwa v167, v193 dst_sel:DWORD dst_unused:UNUSED_PAD src0_sel:WORD_1
	v_pk_mul_f32 v[164:165], v[164:165], s[84:85] op_sel_hi:[1,0]
	v_pk_mul_f32 v[166:167], v[166:167], s[84:85] op_sel_hi:[1,0]
	v_pk_fma_f32 v[20:21], v[20:21], v[132:133], v[164:165]
	v_pk_fma_f32 v[22:23], v[22:23], v[134:135], v[166:167]
	v_cvt_pk_f16_f32 v172, v20, v21
	v_cvt_pk_f16_f32 v173, v22, v23
	v_cvt_f32_f16_e32 v164, v194
	v_cvt_f32_f16_sdwa v165, v194 dst_sel:DWORD dst_unused:UNUSED_PAD src0_sel:WORD_1
	v_cvt_f32_f16_e32 v166, v195
	v_cvt_f32_f16_sdwa v167, v195 dst_sel:DWORD dst_unused:UNUSED_PAD src0_sel:WORD_1
	v_pk_mul_f32 v[164:165], v[164:165], s[84:85] op_sel_hi:[1,0]
	v_pk_mul_f32 v[166:167], v[166:167], s[84:85] op_sel_hi:[1,0]
	v_pk_fma_f32 v[24:25], v[24:25], v[136:137], v[164:165]
	v_pk_fma_f32 v[26:27], v[26:27], v[138:139], v[166:167]
	v_cvt_pk_f16_f32 v174, v24, v25
	v_cvt_pk_f16_f32 v175, v26, v27
	s_nop 1
	v_permlane16_swap_b32_e32 v172, v174
	v_permlane16_swap_b32_e32 v173, v175
	global_store_dwordx4 v177, v[172:175], s[80:81]
	s_waitcnt vmcnt(5)
	v_permlane16_swap_b32_e32 v196, v198
	v_permlane16_swap_b32_e32 v197, v199
	v_cvt_f32_f16_e32 v164, v196
	v_cvt_f32_f16_sdwa v165, v196 dst_sel:DWORD dst_unused:UNUSED_PAD src0_sel:WORD_1
	v_cvt_f32_f16_e32 v166, v197
	v_cvt_f32_f16_sdwa v167, v197 dst_sel:DWORD dst_unused:UNUSED_PAD src0_sel:WORD_1
	v_pk_mul_f32 v[164:165], v[164:165], s[84:85] op_sel_hi:[1,0]
	v_pk_mul_f32 v[166:167], v[166:167], s[84:85] op_sel_hi:[1,0]
	v_pk_fma_f32 v[28:29], v[28:29], v[140:141], v[164:165]
	v_pk_fma_f32 v[30:31], v[30:31], v[142:143], v[166:167]
	v_cvt_pk_f16_f32 v228, v28, v29
	v_cvt_pk_f16_f32 v229, v30, v31
	v_cvt_f32_f16_e32 v164, v198
	v_cvt_f32_f16_sdwa v165, v198 dst_sel:DWORD dst_unused:UNUSED_PAD src0_sel:WORD_1
	v_cvt_f32_f16_e32 v166, v199
	v_cvt_f32_f16_sdwa v167, v199 dst_sel:DWORD dst_unused:UNUSED_PAD src0_sel:WORD_1
	v_pk_mul_f32 v[164:165], v[164:165], s[84:85] op_sel_hi:[1,0]
	v_pk_mul_f32 v[166:167], v[166:167], s[84:85] op_sel_hi:[1,0]
	v_pk_fma_f32 v[32:33], v[32:33], v[144:145], v[164:165]
	v_pk_fma_f32 v[34:35], v[34:35], v[146:147], v[166:167]
	v_cvt_pk_f16_f32 v230, v32, v33
	v_cvt_pk_f16_f32 v231, v34, v35
	s_nop 1
	v_permlane16_swap_b32_e32 v228, v230
	v_permlane16_swap_b32_e32 v229, v231
	global_store_dwordx4 v177, v[228:231], s[80:81] offset:64
	v_add_u32_e32 v177, 0x8000, v177
	v_add_u32_e32 v178, 0x8000, v178
	global_load_dwordx4 v[192:195], v178, s[80:81]
	global_load_dwordx4 v[196:199], v178, s[80:81] offset:64
	s_waitcnt vmcnt(5)
	v_permlane16_swap_b32_e32 v184, v186
	v_permlane16_swap_b32_e32 v185, v187
	v_cvt_f32_f16_e32 v164, v184
	v_cvt_f32_f16_sdwa v165, v184 dst_sel:DWORD dst_unused:UNUSED_PAD src0_sel:WORD_1
	v_cvt_f32_f16_e32 v166, v185
	v_cvt_f32_f16_sdwa v167, v185 dst_sel:DWORD dst_unused:UNUSED_PAD src0_sel:WORD_1
	v_pk_mul_f32 v[164:165], v[164:165], s[84:85] op_sel_hi:[1,0]
	v_pk_mul_f32 v[166:167], v[166:167], s[84:85] op_sel_hi:[1,0]
	v_pk_fma_f32 v[36:37], v[36:37], v[132:133], v[164:165]
	v_pk_fma_f32 v[38:39], v[38:39], v[134:135], v[166:167]
	v_cvt_pk_f16_f32 v172, v36, v37
	v_cvt_pk_f16_f32 v173, v38, v39
	v_cvt_f32_f16_e32 v164, v186
	v_cvt_f32_f16_sdwa v165, v186 dst_sel:DWORD dst_unused:UNUSED_PAD src0_sel:WORD_1
	v_cvt_f32_f16_e32 v166, v187
	v_cvt_f32_f16_sdwa v167, v187 dst_sel:DWORD dst_unused:UNUSED_PAD src0_sel:WORD_1
	v_pk_mul_f32 v[164:165], v[164:165], s[84:85] op_sel_hi:[1,0]
	v_pk_mul_f32 v[166:167], v[166:167], s[84:85] op_sel_hi:[1,0]
	v_pk_fma_f32 v[40:41], v[40:41], v[136:137], v[164:165]
	v_pk_fma_f32 v[42:43], v[42:43], v[138:139], v[166:167]
	v_cvt_pk_f16_f32 v174, v40, v41
	v_cvt_pk_f16_f32 v175, v42, v43
	s_nop 1
	v_permlane16_swap_b32_e32 v172, v174
	v_permlane16_swap_b32_e32 v173, v175
	global_store_dwordx4 v177, v[172:175], s[80:81]
	s_waitcnt vmcnt(5)
	v_permlane16_swap_b32_e32 v188, v190
	v_permlane16_swap_b32_e32 v189, v191
	v_cvt_f32_f16_e32 v164, v188
	v_cvt_f32_f16_sdwa v165, v188 dst_sel:DWORD dst_unused:UNUSED_PAD src0_sel:WORD_1
	v_cvt_f32_f16_e32 v166, v189
	v_cvt_f32_f16_sdwa v167, v189 dst_sel:DWORD dst_unused:UNUSED_PAD src0_sel:WORD_1
	v_pk_mul_f32 v[164:165], v[164:165], s[84:85] op_sel_hi:[1,0]
	v_pk_mul_f32 v[166:167], v[166:167], s[84:85] op_sel_hi:[1,0]
	v_pk_fma_f32 v[44:45], v[44:45], v[140:141], v[164:165]
	v_pk_fma_f32 v[46:47], v[46:47], v[142:143], v[166:167]
	v_cvt_pk_f16_f32 v228, v44, v45
	v_cvt_pk_f16_f32 v229, v46, v47
	v_cvt_f32_f16_e32 v164, v190
	v_cvt_f32_f16_sdwa v165, v190 dst_sel:DWORD dst_unused:UNUSED_PAD src0_sel:WORD_1
	v_cvt_f32_f16_e32 v166, v191
	v_cvt_f32_f16_sdwa v167, v191 dst_sel:DWORD dst_unused:UNUSED_PAD src0_sel:WORD_1
	v_pk_mul_f32 v[164:165], v[164:165], s[84:85] op_sel_hi:[1,0]
	v_pk_mul_f32 v[166:167], v[166:167], s[84:85] op_sel_hi:[1,0]
	v_pk_fma_f32 v[48:49], v[48:49], v[144:145], v[164:165]
	v_pk_fma_f32 v[50:51], v[50:51], v[146:147], v[166:167]
	v_cvt_pk_f16_f32 v230, v48, v49
	v_cvt_pk_f16_f32 v231, v50, v51
	s_nop 1
	v_permlane16_swap_b32_e32 v228, v230
	v_permlane16_swap_b32_e32 v229, v231
	global_store_dwordx4 v177, v[228:231], s[80:81] offset:64
	v_add_u32_e32 v177, 0x8000, v177
	s_waitcnt vmcnt(3)
	v_permlane16_swap_b32_e32 v192, v194
	v_permlane16_swap_b32_e32 v193, v195
	v_cvt_f32_f16_e32 v164, v192
	v_cvt_f32_f16_sdwa v165, v192 dst_sel:DWORD dst_unused:UNUSED_PAD src0_sel:WORD_1
	v_cvt_f32_f16_e32 v166, v193
	v_cvt_f32_f16_sdwa v167, v193 dst_sel:DWORD dst_unused:UNUSED_PAD src0_sel:WORD_1
	v_pk_mul_f32 v[164:165], v[164:165], s[84:85] op_sel_hi:[1,0]
	v_pk_mul_f32 v[166:167], v[166:167], s[84:85] op_sel_hi:[1,0]
	v_pk_fma_f32 v[52:53], v[52:53], v[132:133], v[164:165]
	v_pk_fma_f32 v[54:55], v[54:55], v[134:135], v[166:167]
	v_cvt_pk_f16_f32 v172, v52, v53
	v_cvt_pk_f16_f32 v173, v54, v55
	v_cvt_f32_f16_e32 v164, v194
	v_cvt_f32_f16_sdwa v165, v194 dst_sel:DWORD dst_unused:UNUSED_PAD src0_sel:WORD_1
	v_cvt_f32_f16_e32 v166, v195
	v_cvt_f32_f16_sdwa v167, v195 dst_sel:DWORD dst_unused:UNUSED_PAD src0_sel:WORD_1
	v_pk_mul_f32 v[164:165], v[164:165], s[84:85] op_sel_hi:[1,0]
	v_pk_mul_f32 v[166:167], v[166:167], s[84:85] op_sel_hi:[1,0]
	v_pk_fma_f32 v[56:57], v[56:57], v[136:137], v[164:165]
	v_pk_fma_f32 v[58:59], v[58:59], v[138:139], v[166:167]
	v_cvt_pk_f16_f32 v174, v56, v57
	v_cvt_pk_f16_f32 v175, v58, v59
	s_nop 1
	v_permlane16_swap_b32_e32 v172, v174
	v_permlane16_swap_b32_e32 v173, v175
	global_store_dwordx4 v177, v[172:175], s[80:81]
	s_waitcnt vmcnt(3)
	v_permlane16_swap_b32_e32 v196, v198
	v_permlane16_swap_b32_e32 v197, v199
	v_cvt_f32_f16_e32 v164, v196
	v_cvt_f32_f16_sdwa v165, v196 dst_sel:DWORD dst_unused:UNUSED_PAD src0_sel:WORD_1
	v_cvt_f32_f16_e32 v166, v197
	v_cvt_f32_f16_sdwa v167, v197 dst_sel:DWORD dst_unused:UNUSED_PAD src0_sel:WORD_1
	v_pk_mul_f32 v[164:165], v[164:165], s[84:85] op_sel_hi:[1,0]
	v_pk_mul_f32 v[166:167], v[166:167], s[84:85] op_sel_hi:[1,0]
	v_pk_fma_f32 v[60:61], v[60:61], v[140:141], v[164:165]
	v_pk_fma_f32 v[62:63], v[62:63], v[142:143], v[166:167]
	v_cvt_pk_f16_f32 v228, v60, v61
	v_cvt_pk_f16_f32 v229, v62, v63
	v_cvt_f32_f16_e32 v164, v198
	v_cvt_f32_f16_sdwa v165, v198 dst_sel:DWORD dst_unused:UNUSED_PAD src0_sel:WORD_1
	v_cvt_f32_f16_e32 v166, v199
	v_cvt_f32_f16_sdwa v167, v199 dst_sel:DWORD dst_unused:UNUSED_PAD src0_sel:WORD_1
	v_pk_mul_f32 v[164:165], v[164:165], s[84:85] op_sel_hi:[1,0]
	v_pk_mul_f32 v[166:167], v[166:167], s[84:85] op_sel_hi:[1,0]
	v_pk_fma_f32 v[64:65], v[64:65], v[144:145], v[164:165]
	v_pk_fma_f32 v[66:67], v[66:67], v[146:147], v[166:167]
	v_cvt_pk_f16_f32 v230, v64, v65
	v_cvt_pk_f16_f32 v231, v66, v67
	s_nop 1
	v_permlane16_swap_b32_e32 v228, v230
	v_permlane16_swap_b32_e32 v229, v231
	global_store_dwordx4 v177, v[228:231], s[80:81] offset:64
	s_nop 1
	s_addk_i32 s25, 0x1000
	s_add_i32 s24, s24, 4
	s_add_i32 s28, s34, 32
	s_cmp_gt_u32 s34, 31
	s_mov_b32 s34, s28
	s_cbranch_scc1 .LBB0_743
	s_branch .LBB0_182
